# FoX loop: 15 packed v_pk_mul between the PV MFMAs split into scalar v_mul pairs (doc 7.5 packed-vs-scalar beside MFMA)
# baseline (speedup 1.0000x reference)
; __device__ __forceinline__ float ex2(float x) { return __builtin_amdgcn_exp2f(x); }
; template <bool FOX> ...
;     ...
;     for (int qt = 0; qt < 2; ++qt) {
;       float mx = fmaxf(fmaxf(st[qt][0], st[qt][1]), fmaxf(st[qt][2], st[qt][3]));
; #pragma unroll
;       for (int r = 4; r < 16; r += 4) mx = fmaxf(fmaxf(mx, st[qt][r]), fmaxf(fmaxf(st[qt][r + 1], st[qt][r + 2]), st[qt][r + 3]));
;       mx = xmax32(mx);
;       const float mnew = fmaxf(mrun[qt], mx);
;       const float alpha = ex2(mrun[qt] - mnew);
;       mrun[qt] = mnew;
;       float ps0 = 0.f, ps1 = 0.f;
; #pragma unroll
;       for (int r = 0; r < 16; r += 2) {
;         float p0 = ex2(st[qt][r] - mnew), p1 = ex2(st[qt][r + 1] - mnew);
;         ps0 += p0; ps1 += p1;
;         st[qt][r] = p0; st[qt][r + 1] = p1;
;       }
;       lrun[qt] = lrun[qt] * alpha + (ps0 + ps1);
; #pragma unroll
;       for (int dt = 0; dt < 2; ++dt) o[dt][qt] = o[dt][qt] * alpha;
; #pragma unroll
;       for (int ks = 0; ks < 2; ++ks) {
;         union { bf16x8 v; uint32_t w[4]; } u;
; #pragma unroll
;         for (int e = 0; e < 4; ++e) u.w[e] = pack2(st[qt][8 * ks + 2 * e], st[qt][8 * ks + 2 * e + 1]);
;         bp[qt][ks] = u.v;
;       }
;     }
.LBB0_512:
	s_nop 7
	v_max_f32_e32 v182, v98, v99
	v_max3_f32 v182, v96, v97, v182
	v_max3_f32 v194, v101, v102, v103
	v_max3_f32 v182, v182, v100, v194
	v_max3_f32 v194, v105, v106, v107
	v_max3_f32 v182, v182, v104, v194
	v_max3_f32 v194, v109, v110, v111
	v_max3_f32 v182, v182, v108, v194
	v_mov_b32_e32 v194, v182
	s_nop 1
	v_permlane32_swap_b32_e32 v182, v194
	v_max3_f32 v182, v185, v182, v194
	v_pk_add_f32 v[96:97], v[96:97], v[182:183] op_sel_hi:[1,0] neg_lo:[0,1] neg_hi:[0,1]
	v_pk_add_f32 v[98:99], v[98:99], v[182:183] op_sel_hi:[1,0] neg_lo:[0,1] neg_hi:[0,1]
	v_pk_add_f32 v[100:101], v[100:101], v[182:183] op_sel_hi:[1,0] neg_lo:[0,1] neg_hi:[0,1]
	v_pk_add_f32 v[102:103], v[102:103], v[182:183] op_sel_hi:[1,0] neg_lo:[0,1] neg_hi:[0,1]
	v_exp_f32_e32 v194, v96
	v_exp_f32_e32 v196, v97
	v_exp_f32_e32 v198, v98
	v_exp_f32_e32 v200, v99
	v_exp_f32_e32 v202, v100
	v_exp_f32_e32 v204, v101
	v_exp_f32_e32 v206, v102
	v_exp_f32_e32 v208, v103
	v_pk_add_f32 v[96:97], v[104:105], v[182:183] op_sel_hi:[1,0] neg_lo:[0,1] neg_hi:[0,1]
	v_pk_add_f32 v[106:107], v[106:107], v[182:183] op_sel_hi:[1,0] neg_lo:[0,1] neg_hi:[0,1]
	v_pk_add_f32 v[108:109], v[108:109], v[182:183] op_sel_hi:[1,0] neg_lo:[0,1] neg_hi:[0,1]
	v_pk_add_f32 v[110:111], v[110:111], v[182:183] op_sel_hi:[1,0] neg_lo:[0,1] neg_hi:[0,1]
	v_max_f32_e32 v104, v82, v83
	v_max3_f32 v104, v80, v81, v104
	v_max3_f32 v105, v85, v86, v87
	v_max3_f32 v104, v104, v84, v105
	v_max3_f32 v105, v89, v90, v91
	v_max3_f32 v104, v104, v88, v105
	v_max3_f32 v105, v93, v94, v95
	v_max3_f32 v104, v104, v92, v105
	v_mov_b32_e32 v105, v104
	s_nop 1
	v_permlane32_swap_b32_e32 v104, v105
	v_max3_f32 v104, v113, v104, v105
	v_exp_f32_e32 v210, v96
	v_exp_f32_e32 v212, v97
	v_exp_f32_e32 v106, v106
	v_exp_f32_e32 v214, v107
	v_exp_f32_e32 v108, v108
	v_exp_f32_e32 v216, v109
	v_exp_f32_e32 v110, v110
	v_exp_f32_e32 v234, v111
	v_pk_add_f32 v[80:81], v[80:81], v[104:105] op_sel_hi:[1,0] neg_lo:[0,1] neg_hi:[0,1]
	v_pk_add_f32 v[82:83], v[82:83], v[104:105] op_sel_hi:[1,0] neg_lo:[0,1] neg_hi:[0,1]
	v_pk_add_f32 v[84:85], v[84:85], v[104:105] op_sel_hi:[1,0] neg_lo:[0,1] neg_hi:[0,1]
	v_pk_add_f32 v[86:87], v[86:87], v[104:105] op_sel_hi:[1,0] neg_lo:[0,1] neg_hi:[0,1]
	v_pk_add_f32 v[88:89], v[88:89], v[104:105] op_sel_hi:[1,0] neg_lo:[0,1] neg_hi:[0,1]
	v_pk_add_f32 v[90:91], v[90:91], v[104:105] op_sel_hi:[1,0] neg_lo:[0,1] neg_hi:[0,1]
	v_pk_add_f32 v[92:93], v[92:93], v[104:105] op_sel_hi:[1,0] neg_lo:[0,1] neg_hi:[0,1]
	v_pk_add_f32 v[94:95], v[94:95], v[104:105] op_sel_hi:[1,0] neg_lo:[0,1] neg_hi:[0,1]
	v_exp_f32_e32 v195, v80
	v_exp_f32_e32 v197, v81
	v_exp_f32_e32 v199, v82
	v_exp_f32_e32 v201, v83
	v_exp_f32_e32 v203, v84
	v_exp_f32_e32 v205, v85
	v_exp_f32_e32 v207, v86
	v_exp_f32_e32 v209, v87
	v_exp_f32_e32 v211, v88
	v_exp_f32_e32 v213, v89
	v_exp_f32_e32 v107, v90
	v_exp_f32_e32 v215, v91
	v_exp_f32_e32 v109, v92
	v_exp_f32_e32 v217, v93
	v_exp_f32_e32 v111, v94
	v_exp_f32_e32 v235, v95
	v_sub_f32_e32 v185, v185, v182
	v_pk_add_f32 v[80:81], v[194:195], 0 op_sel_hi:[1,0]
	v_pk_add_f32 v[82:83], v[196:197], 0 op_sel_hi:[1,0]
	v_exp_f32_e32 v236, v185
	v_pk_add_f32 v[80:81], v[198:199], v[80:81]
	v_pk_add_f32 v[82:83], v[200:201], v[82:83]
	v_pk_add_f32 v[80:81], v[202:203], v[80:81]
	v_pk_add_f32 v[82:83], v[204:205], v[82:83]
	v_pk_add_f32 v[80:81], v[206:207], v[80:81]
	v_pk_add_f32 v[82:83], v[208:209], v[82:83]
	v_sub_f32_e32 v105, v113, v104
	v_pk_add_f32 v[80:81], v[210:211], v[80:81]
	v_pk_add_f32 v[82:83], v[212:213], v[82:83]
	v_pk_mul_f32 v[62:63], v[62:63], v[236:237] op_sel_hi:[1,0]
	v_pk_mul_f32 v[60:61], v[60:61], v[236:237] op_sel_hi:[1,0]
	v_pk_mul_f32 v[58:59], v[58:59], v[236:237] op_sel_hi:[1,0]
	v_pk_mul_f32 v[56:57], v[56:57], v[236:237] op_sel_hi:[1,0]
	v_pk_mul_f32 v[54:55], v[54:55], v[236:237] op_sel_hi:[1,0]
	v_pk_mul_f32 v[52:53], v[52:53], v[236:237] op_sel_hi:[1,0]
	v_pk_mul_f32 v[50:51], v[50:51], v[236:237] op_sel_hi:[1,0]
	v_pk_mul_f32 v[48:49], v[48:49], v[236:237] op_sel_hi:[1,0]
	v_pk_mul_f32 v[46:47], v[46:47], v[236:237] op_sel_hi:[1,0]
	v_pk_mul_f32 v[44:45], v[44:45], v[236:237] op_sel_hi:[1,0]
	v_pk_mul_f32 v[42:43], v[42:43], v[236:237] op_sel_hi:[1,0]
	v_pk_mul_f32 v[40:41], v[40:41], v[236:237] op_sel_hi:[1,0]
	v_pk_mul_f32 v[38:39], v[38:39], v[236:237] op_sel_hi:[1,0]
	v_pk_mul_f32 v[36:37], v[36:37], v[236:237] op_sel_hi:[1,0]
	v_pk_mul_f32 v[34:35], v[34:35], v[236:237] op_sel_hi:[1,0]
	v_pk_mul_f32 v[32:33], v[32:33], v[236:237] op_sel_hi:[1,0]
	v_exp_f32_e32 v237, v105
	v_pk_add_f32 v[80:81], v[106:107], v[80:81]
	v_pk_add_f32 v[82:83], v[214:215], v[82:83]
	v_pk_add_f32 v[80:81], v[108:109], v[80:81]
	v_pk_add_f32 v[82:83], v[216:217], v[82:83]
	v_pk_add_f32 v[80:81], v[110:111], v[80:81]
	v_pk_add_f32 v[82:83], v[234:235], v[82:83]
	v_cvt_pk_bf16_f32 v100, v194, v196
	v_cvt_pk_bf16_f32 v101, v198, v200
	v_cvt_pk_bf16_f32 v102, v202, v204
	v_cvt_pk_bf16_f32 v103, v206, v208
	v_cvt_pk_bf16_f32 v84, v195, v197
	s_nop 0
	v_pk_add_f32 v[80:81], v[80:81], v[82:83]
	v_cvt_pk_bf16_f32 v85, v199, v201
	v_cvt_pk_bf16_f32 v86, v203, v205
	v_cvt_pk_bf16_f32 v87, v207, v209
	s_waitcnt vmcnt(3)
; template <bool FOX> ...
;     ...
;       lrun[qt] = lrun[qt] * alpha + (ps0 + ps1);
; #pragma unroll
;       for (int dt = 0; dt < 2; ++dt) o[dt][qt] = o[dt][qt] * alpha;
; #pragma unroll
;       for (int ks = 0; ks < 2; ++ks) {
;         union { bf16x8 v; uint32_t w[4]; } u;
; #pragma unroll
;         for (int e = 0; e < 4; ++e) u.w[e] = pack2(st[qt][8 * ks + 2 * e], st[qt][8 * ks + 2 * e + 1]);
;         bp[qt][ks] = u.v;
;       }
;     }
; #pragma unroll
;     for (int dt = 0; dt < 2; ++dt)
; #pragma unroll
;       for (int qt = 0; qt < 2; ++qt)
; #pragma unroll
;         for (int ks = 0; ks < 2; ++ks) o[dt][qt] = mfma32(av[dt][ks], bp[qt][ks], o[dt][qt]);
	v_mfma_f32_32x32x16_bf16 v[48:63], v[174:177], v[100:103], v[48:63]
	v_fma_f32 v188, v188, v236, v80
	v_fma_f32 v189, v189, v237, v81
	v_mov_b32_e32 v80, v237
	v_mul_f32_e64 v30, v30, v80
	v_mul_f32_e64 v31, v31, v80
	v_mul_f32_e32 v28, v28, v80
	v_mul_f32_e32 v29, v29, v80
	v_mul_f32_e32 v26, v26, v80
	v_mul_f32_e32 v27, v27, v80
	v_mul_f32_e32 v24, v24, v80
	v_mul_f32_e32 v25, v25, v80
	v_mul_f32_e32 v22, v22, v80
	v_mul_f32_e32 v23, v23, v80
	v_mul_f32_e32 v20, v20, v80
	v_mul_f32_e32 v21, v21, v80
	v_mul_f32_e32 v18, v18, v80
	v_mul_f32_e32 v19, v19, v80
	v_mul_f32_e32 v16, v16, v80
	v_mul_f32_e32 v17, v17, v80
	v_mul_f32_e32 v14, v14, v80
	v_mul_f32_e32 v15, v15, v80
	v_mul_f32_e32 v12, v12, v80
	v_mul_f32_e32 v13, v13, v80
	v_mul_f32_e32 v10, v10, v80
	v_mul_f32_e32 v11, v11, v80
	v_mul_f32_e32 v8, v8, v80
	v_mul_f32_e32 v9, v9, v80
	v_mul_f32_e32 v6, v6, v80
	v_mul_f32_e32 v7, v7, v80
	v_mul_f32_e32 v4, v4, v80
	v_mul_f32_e32 v5, v5, v80
	v_mul_f32_e32 v2, v2, v80
	v_mul_f32_e32 v3, v3, v80
	v_mul_f32_e32 v0, v0, v80
	v_mul_f32_e32 v1, v1, v80
	v_mfma_f32_32x32x16_bf16 v[16:31], v[174:177], v[84:87], v[16:31]
	v_cvt_pk_bf16_f32 v96, v210, v212
	v_cvt_pk_bf16_f32 v97, v106, v214
	v_cvt_pk_bf16_f32 v98, v108, v216
	v_cvt_pk_bf16_f32 v99, v110, v234
	v_cvt_pk_bf16_f32 v80, v211, v213
	v_cvt_pk_bf16_f32 v81, v107, v215
	v_cvt_pk_bf16_f32 v82, v109, v217
	s_waitcnt vmcnt(1)
	v_mfma_f32_32x32x16_bf16 v[32:47], v[166:169], v[100:103], v[32:47]
	v_cvt_pk_bf16_f32 v83, v111, v235
	s_add_i32 s10, s10, 32
	v_lshl_add_u64 v[190:191], v[190:191], 0, s[68:69]
	v_lshl_add_u64 v[192:193], v[192:193], 0, s[86:87]
	s_cmp_eq_u32 s8, s9
	v_mfma_f32_32x32x16_bf16 v[0:15], v[166:169], v[84:87], v[0:15]
	v_mfma_f32_32x32x16_bf16 v[48:63], v[170:173], v[96:99], v[48:63]
	v_mfma_f32_32x32x16_bf16 v[16:31], v[170:173], v[80:83], v[16:31]
	s_waitcnt vmcnt(0)
	v_mfma_f32_32x32x16_bf16 v[32:47], v[162:165], v[96:99], v[32:47]
	v_mfma_f32_32x32x16_bf16 v[0:15], v[162:165], v[80:83], v[0:15]
	s_cbranch_scc1 .LBB0_505
	v_mov_b32_e32 v185, v182
	v_mov_b32_e32 v113, v104
	s_branch .LBB0_508
